# dn GEMM: ctx tail tiles split 4-way along K across 32 CUs, partial sums added in the following LayerNorm row pass; plus attention K-frag hoist and nop trimming
# speedup vs baseline: 1.0198x; 1.0089x over previous
.LBB0_228:
	s_or_b64 exec, exec, s[0:1]
	s_xor_b64 s[0:1], s[4:5], -1
	s_mov_b32 s101, 0
	s_mov_b32 s100, 0
	s_mov_b32 s99, -2
	s_mov_b32 s98, -2
	s_cmp_lg_u32 s36, 0x82
	s_cbranch_scc1 .Ldnt_e0
	s_mov_b32 s36, 0x80
	s_mov_b32 s101, 1
.Ldnt_e0:
	s_lshl_b32 s6, s36, 2
	s_lshl_b32 s7, s101, 5
	s_add_i32 s6, s6, s7
	v_writelane_b32 v255, s0, 19
	v_mov_b32_e32 v10, v222
	s_cmp_lt_i32 s78, s6
	v_writelane_b32 v255, s1, 20
	s_waitcnt lgkmcnt(0)
	s_barrier
	s_cselect_b64 s[0:1], -1, 0
	s_cmp_ge_i32 s78, s6
	v_readfirstlane_b32 s7, v10
	s_cbranch_scc1 .LBB0_230
	s_lshr_b32 s2, s36, 1
	v_readlane_b32 s3, v253, 4
	s_add_i32 s2, s2, s3
	v_readlane_b32 s3, v253, 3
	s_mul_i32 s2, s2, s3
	v_readlane_b32 s3, v253, 2
	s_add_i32 s2, s2, s3
	s_ashr_i32 s8, s2, 31
	s_lshr_b32 s8, s8, 27
	s_add_i32 s8, s2, s8
	s_ashr_i32 s9, s8, 5
	s_lshl_b32 s9, s9, 3
	s_sub_i32 s10, s36, s9
	s_min_i32 s10, s10, 8
	s_abs_i32 s11, s10
	v_cvt_f32_u32_e32 v1, s11
	s_sub_i32 s13, 0, s11
	s_andn2_b32 s8, s8, 31
	s_sub_i32 s8, s2, s8
	v_rcp_iflag_f32_e32 v1, v1
	s_abs_i32 s2, s8
	s_xor_b32 s12, s8, s10
	s_ashr_i32 s12, s12, 31
	v_mul_f32_e32 v1, 0x4f7ffffe, v1
	v_cvt_u32_f32_e32 v1, v1
	s_nop 0
	v_readfirstlane_b32 s14, v1
	s_mul_i32 s13, s13, s14
	s_mul_hi_u32 s13, s14, s13
	s_add_i32 s14, s14, s13
	s_mul_hi_u32 s13, s2, s14
	s_mul_i32 s14, s13, s11
	s_sub_i32 s2, s2, s14
	s_add_i32 s15, s13, 1
	s_sub_i32 s14, s2, s11
	s_cmp_ge_u32 s2, s11
	s_cselect_b32 s13, s15, s13
	s_cselect_b32 s2, s14, s2
	s_add_i32 s14, s13, 1
	s_cmp_ge_u32 s2, s11
	s_cselect_b32 s2, s14, s13
	s_xor_b32 s2, s2, s12
	s_sub_i32 s2, s2, s12
	s_mul_i32 s10, s2, s10
	s_sub_i32 s8, s8, s10
	s_add_i32 s3, s9, s8

.LBB0_236:
	s_mov_b32 s99, s98
	s_mov_b32 s98, -2
	s_bfe_u32 s100, s100, 0x40008
	s_add_i32 s64, s64, 1
	s_mul_i32 s0, s64, s83
	s_mul_hi_u32 s1, s64, s58
	s_add_i32 s1, s1, s0
	s_mul_i32 s0, s64, s58
	s_add_u32 s0, s0, s78
	s_addc_u32 s1, s1, s82
	v_mov_b64_e32 v[2:3], s[6:7]
	v_cmp_ge_i64_e32 vcc, s[0:1], v[2:3]
	v_cmp_lt_i64_e64 s[4:5], s[0:1], v[2:3]
	s_cbranch_vccnz .LBB0_238
	s_cmp_eq_u32 s101, 0
	s_cbranch_scc1 .Ldnt_stddec
	s_cmp_lt_u32 s0, 0x200
	s_cbranch_scc1 .Ldnt_stddec
	s_sub_u32 s74, s0, 0x200
	s_lshr_b32 s75, s74, 3
	s_and_b32 s74, s74, 7
	s_and_b32 s66, s74, 1
	s_add_i32 s66, s66, 0x80
	s_lshr_b32 s61, s74, 1
	s_cmp_ge_u32 s75, 2
	s_cselect_b32 s98, 32, 30
	s_mul_i32 s74, s75, 0x600
	s_cmp_eq_u32 s75, 3
	s_cselect_b32 s74, 0x1100, s74
	s_lshl_b32 s75, s75, 8
	s_or_b32 s100, s100, s75
	s_lshl_b32 s74, s74, 16
	s_or_b32 s100, s100, s74
	s_branch .LBB0_238
.Ldnt_stddec:
	s_ashr_i32 s1, s0, 31
	s_lshr_b32 s1, s1, 29
	s_add_i32 s1, s0, s1
	s_ashr_i32 s22, s1, 3
	s_and_b32 s1, s1, -8
	s_sub_i32 s0, s0, s1
	s_lshr_b32 s1, s0, 31
	s_add_i32 s1, s60, s1
	s_mul_i32 s0, s1, s0
	s_add_i32 s0, s0, s22
	s_ashr_i32 s1, s0, 31
	s_lshr_b32 s1, s1, 27
	s_add_i32 s1, s0, s1
	s_ashr_i32 s22, s1, 5
	s_lshl_b32 s22, s22, 3
	s_sub_i32 s23, s36, s22
	s_min_i32 s23, s23, 8
	s_abs_i32 s34, s23
	v_cvt_f32_u32_e32 v2, s34
	s_sub_i32 s74, 0, s34
	s_andn2_b32 s1, s1, 31
	s_sub_i32 s0, s0, s1
	v_rcp_iflag_f32_e32 v2, v2
	s_abs_i32 s1, s0
	s_xor_b32 s35, s0, s23
	s_ashr_i32 s35, s35, 31
	v_mul_f32_e32 v2, 0x4f7ffffe, v2
	v_cvt_u32_f32_e32 v2, v2
	s_nop 0
	v_readfirstlane_b32 s75, v2
	s_mul_i32 s74, s74, s75
	s_mul_hi_u32 s74, s75, s74
	s_add_i32 s75, s75, s74
	s_mul_hi_u32 s74, s1, s75
	s_mul_i32 s75, s74, s34
	s_sub_i32 s1, s1, s75
	s_add_i32 s77, s74, 1
	s_sub_i32 s75, s1, s34
	s_cmp_ge_u32 s1, s34
	s_cselect_b32 s74, s77, s74
	s_cselect_b32 s1, s75, s1
	s_add_i32 s75, s74, 1
	s_cmp_ge_u32 s1, s34
	s_cselect_b32 s1, s75, s74
	s_xor_b32 s1, s1, s35
	s_sub_i32 s61, s1, s35
	s_mul_i32 s1, s61, s23
	s_sub_i32 s0, s0, s1
	s_add_i32 s66, s0, s22
.LBB0_238:
	s_nop 0
	v_cndmask_b32_e64 v2, 0, 1, s[4:5]
	v_cmp_ne_u32_e64 s[0:1], 1, v2
	s_andn2_b64 vcc, exec, s[4:5]
	s_mov_b64 s[34:35], s[24:25]
	s_cbranch_vccnz .LBB0_240
	s_mul_i32 s5, s66, 0x160000
	v_readlane_b32 s22, v253, 60
	s_mul_hi_i32 s4, s66, 0x160000
	v_readlane_b32 s23, v253, 61
	s_add_u32 s34, s22, s5
	s_addc_u32 s35, s23, s4
	s_lshr_b32 s74, s100, 16
	s_add_u32 s34, s34, s74
	s_addc_u32 s35, s35, 0
.LBB0_240:
	s_and_b64 vcc, exec, s[0:1]
	s_mov_b64 s[22:23], s[26:27]
	s_cbranch_vccnz .LBB0_242
	s_mul_i32 s5, s61, 0x160000
	s_mul_hi_i32 s4, s61, 0x160000
	s_add_u32 s22, s19, s5
	s_addc_u32 s23, s28, s4
	s_lshr_b32 s74, s100, 16
	s_add_u32 s22, s22, s74
	s_addc_u32 s23, s23, 0
.LBB0_242:
	s_add_u32 s77, s26, 0x100
	v_mov_b32_e32 v2, 0
	s_addc_u32 s78, s27, 0
	s_mov_b32 s79, s99
	v_mov_b32_e32 v3, v2
	v_mov_b32_e32 v4, v2
	v_mov_b32_e32 v5, v2
	v_mov_b32_e32 v34, v2
	v_mov_b32_e32 v35, v2
	v_mov_b32_e32 v36, v2
	v_mov_b32_e32 v37, v2
	v_mov_b32_e32 v6, v2
	v_mov_b32_e32 v7, v2
	v_mov_b32_e32 v8, v2
	v_mov_b32_e32 v9, v2
	v_mov_b32_e32 v38, v2
	v_mov_b32_e32 v39, v2
	v_mov_b32_e32 v40, v2
	v_mov_b32_e32 v41, v2
	v_mov_b32_e32 v10, v2
	v_mov_b32_e32 v11, v2
	v_mov_b32_e32 v12, v2
	v_mov_b32_e32 v13, v2
	v_mov_b32_e32 v42, v2
	v_mov_b32_e32 v43, v2
	v_mov_b32_e32 v44, v2
	v_mov_b32_e32 v45, v2
	v_mov_b32_e32 v14, v2
	v_mov_b32_e32 v15, v2
	v_mov_b32_e32 v16, v2
	v_mov_b32_e32 v17, v2
	v_mov_b32_e32 v46, v2
	v_mov_b32_e32 v47, v2
	v_mov_b32_e32 v48, v2
	v_mov_b32_e32 v49, v2
	v_mov_b32_e32 v66, v2
	v_mov_b32_e32 v67, v2
	v_mov_b32_e32 v68, v2
	v_mov_b32_e32 v69, v2
	v_mov_b32_e32 v98, v2
	v_mov_b32_e32 v99, v2
	v_mov_b32_e32 v100, v2
	v_mov_b32_e32 v101, v2
	v_mov_b32_e32 v70, v2
	v_mov_b32_e32 v71, v2
	v_mov_b32_e32 v72, v2
	v_mov_b32_e32 v73, v2
	v_mov_b32_e32 v102, v2
	v_mov_b32_e32 v103, v2
	v_mov_b32_e32 v104, v2
	v_mov_b32_e32 v105, v2
	v_mov_b32_e32 v74, v2
	v_mov_b32_e32 v75, v2
	v_mov_b32_e32 v76, v2
	v_mov_b32_e32 v77, v2
	v_mov_b32_e32 v106, v2
	v_mov_b32_e32 v107, v2
	v_mov_b32_e32 v108, v2
	v_mov_b32_e32 v109, v2
	v_mov_b32_e32 v78, v2
	v_mov_b32_e32 v79, v2
	v_mov_b32_e32 v80, v2
	v_mov_b32_e32 v81, v2
	v_mov_b32_e32 v110, v2
	v_mov_b32_e32 v111, v2
	v_mov_b32_e32 v112, v2
	v_mov_b32_e32 v113, v2
	v_mov_b32_e32 v18, v2
	v_mov_b32_e32 v19, v2
	v_mov_b32_e32 v20, v2
	v_mov_b32_e32 v21, v2
	v_mov_b32_e32 v50, v2
	v_mov_b32_e32 v51, v2
	v_mov_b32_e32 v52, v2
	v_mov_b32_e32 v53, v2
	v_mov_b32_e32 v22, v2
	v_mov_b32_e32 v23, v2
	v_mov_b32_e32 v24, v2
	v_mov_b32_e32 v25, v2
	v_mov_b32_e32 v54, v2
	v_mov_b32_e32 v55, v2
	v_mov_b32_e32 v56, v2
	v_mov_b32_e32 v57, v2
	v_mov_b32_e32 v26, v2
	v_mov_b32_e32 v27, v2
	v_mov_b32_e32 v28, v2
	v_mov_b32_e32 v29, v2
	v_mov_b32_e32 v58, v2
	v_mov_b32_e32 v59, v2
	v_mov_b32_e32 v60, v2
	v_mov_b32_e32 v61, v2
	v_mov_b32_e32 v30, v2
	v_mov_b32_e32 v31, v2
	v_mov_b32_e32 v32, v2
	v_mov_b32_e32 v33, v2
	v_mov_b32_e32 v62, v2
	v_mov_b32_e32 v63, v2
	v_mov_b32_e32 v64, v2
	v_mov_b32_e32 v65, v2
	v_mov_b32_e32 v82, v2
	v_mov_b32_e32 v83, v2
	v_mov_b32_e32 v84, v2
	v_mov_b32_e32 v85, v2
	v_mov_b32_e32 v114, v2
	v_mov_b32_e32 v115, v2
	v_mov_b32_e32 v116, v2
	v_mov_b32_e32 v117, v2
	v_mov_b32_e32 v86, v2
	v_mov_b32_e32 v87, v2
	v_mov_b32_e32 v88, v2
	v_mov_b32_e32 v89, v2
	v_mov_b32_e32 v118, v2
	v_mov_b32_e32 v119, v2
	v_mov_b32_e32 v120, v2
	v_mov_b32_e32 v121, v2
	v_mov_b32_e32 v90, v2
	v_mov_b32_e32 v91, v2
	v_mov_b32_e32 v92, v2
	v_mov_b32_e32 v93, v2
	v_mov_b32_e32 v122, v2
	v_mov_b32_e32 v123, v2
	v_mov_b32_e32 v124, v2
	v_mov_b32_e32 v125, v2
	v_mov_b32_e32 v94, v2
	v_mov_b32_e32 v95, v2
	v_mov_b32_e32 v96, v2
	v_mov_b32_e32 v97, v2
	v_mov_b32_e32 v126, v2
	v_mov_b32_e32 v127, v2
	v_mov_b32_e32 v128, v2
	v_mov_b32_e32 v129, v2

.LBB0_250:
	s_and_b32 s92, s100, 15
	s_cmp_eq_u32 s92, 0
	s_cbranch_scc1 .Ldnt_epi
	s_add_i32 s10, s3, 0xffffff80
	s_lshl_b32 s10, s10, 20
	s_sub_u32 s68, s96, s10
	s_subb_u32 s69, s97, 0
	s_add_i32 s92, s92, -1
	s_lshl_b32 s92, s92, 21
	s_add_u32 s92, s92, 0x17700000
	s_add_u32 s96, s96, s92
	s_addc_u32 s97, s97, 0
	s_sub_u32 s10, s68, 0x13ec00
	s_subb_u32 s11, s69, 0
	s_mov_b64 s[12:13], s[10:11]
	s_sub_u32 s68, s68, 0x17fc00
	s_subb_u32 s69, s69, 0
	s_mov_b64 s[14:15], exec

.LBB0_336:
	s_add_i32 s10, s6, 0xffff8000
	s_and_b64 s[0:1], s[0:1], exec
	s_cselect_b32 s1, s7, 0
	s_cselect_b32 s0, s6, s10
	s_cselect_b32 s11, s75, s12
	s_cselect_b32 s10, s74, s2
	s_lshl_b64 s[0:1], s[0:1], 12
	s_add_u32 s10, s10, s0
	s_addc_u32 s11, s11, s1
	global_load_dwordx4 v[80:83], v92, s[10:11]
	global_load_dwordx4 v[76:79], v92, s[10:11] offset:1024
	global_load_dwordx4 v[72:75], v92, s[10:11] offset:2048
	global_load_dwordx4 v[68:71], v92, s[10:11] offset:3072
	s_cmp_lt_i32 s6, 0x8000
	s_cbranch_scc1 .Lfxa_skip
	s_add_u32 s100, s10, 0x17700000
	s_addc_u32 s101, s11, 0
	global_load_dwordx4 v[130:133], v92, s[100:101]
	global_load_dwordx4 v[134:137], v92, s[100:101] offset:1024
	global_load_dwordx4 v[138:141], v92, s[100:101] offset:2048
	global_load_dwordx4 v[142:145], v92, s[100:101] offset:3072
	s_add_u32 s100, s100, 0x200000
	s_addc_u32 s101, s101, 0
	global_load_dwordx4 v[146:149], v92, s[100:101]
	global_load_dwordx4 v[150:153], v92, s[100:101] offset:1024
	global_load_dwordx4 v[154:157], v92, s[100:101] offset:2048
	global_load_dwordx4 v[158:161], v92, s[100:101] offset:3072
	s_add_u32 s100, s100, 0x200000
	s_addc_u32 s101, s101, 0
	global_load_dwordx4 v[162:165], v92, s[100:101]
	global_load_dwordx4 v[166:169], v92, s[100:101] offset:1024
	global_load_dwordx4 v[170:173], v92, s[100:101] offset:2048
	global_load_dwordx4 v[174:177], v92, s[100:101] offset:3072
	s_waitcnt vmcnt(0)
	v_add_f32_e32 v80, v80, v130
	v_add_f32_e32 v81, v81, v131
	v_add_f32_e32 v82, v82, v132
	v_add_f32_e32 v83, v83, v133
	v_add_f32_e32 v76, v76, v134
	v_add_f32_e32 v77, v77, v135
	v_add_f32_e32 v78, v78, v136
	v_add_f32_e32 v79, v79, v137
	v_add_f32_e32 v72, v72, v138
	v_add_f32_e32 v73, v73, v139
	v_add_f32_e32 v74, v74, v140
	v_add_f32_e32 v75, v75, v141
	v_add_f32_e32 v68, v68, v142
	v_add_f32_e32 v69, v69, v143
	v_add_f32_e32 v70, v70, v144
	v_add_f32_e32 v71, v71, v145
	v_add_f32_e32 v80, v80, v146
	v_add_f32_e32 v81, v81, v147
	v_add_f32_e32 v82, v82, v148
	v_add_f32_e32 v83, v83, v149
	v_add_f32_e32 v76, v76, v150
	v_add_f32_e32 v77, v77, v151
	v_add_f32_e32 v78, v78, v152
	v_add_f32_e32 v79, v79, v153
	v_add_f32_e32 v72, v72, v154
	v_add_f32_e32 v73, v73, v155
	v_add_f32_e32 v74, v74, v156
	v_add_f32_e32 v75, v75, v157
	v_add_f32_e32 v68, v68, v158
	v_add_f32_e32 v69, v69, v159
	v_add_f32_e32 v70, v70, v160
	v_add_f32_e32 v71, v71, v161
	v_add_f32_e32 v80, v80, v162
	v_add_f32_e32 v81, v81, v163
	v_add_f32_e32 v82, v82, v164
	v_add_f32_e32 v83, v83, v165
	v_add_f32_e32 v76, v76, v166
	v_add_f32_e32 v77, v77, v167
	v_add_f32_e32 v78, v78, v168
	v_add_f32_e32 v79, v79, v169
	v_add_f32_e32 v72, v72, v170
	v_add_f32_e32 v73, v73, v171
	v_add_f32_e32 v74, v74, v172
	v_add_f32_e32 v75, v75, v173
	v_add_f32_e32 v68, v68, v174
	v_add_f32_e32 v69, v69, v175
	v_add_f32_e32 v70, v70, v176
	v_add_f32_e32 v71, v71, v177
	global_store_dwordx4 v92, v[80:83], s[10:11]
	global_store_dwordx4 v92, v[76:79], s[10:11] offset:1024
	global_store_dwordx4 v92, v[72:75], s[10:11] offset:2048
	global_store_dwordx4 v92, v[68:71], s[10:11] offset:3072
	s_nop 1
.Lfxa_skip:
	s_waitcnt vmcnt(3)
	v_mov_b32_e32 v2, v81
	v_mov_b32_e32 v3, v82
	v_mov_b32_e32 v84, v80
	v_mov_b32_e32 v85, v83
	v_pk_add_f32 v[2:3], v[2:3], v[84:85]
	s_waitcnt vmcnt(2)
	v_mov_b32_e32 v84, v77
	v_mov_b32_e32 v85, v78
	v_mov_b32_e32 v94, v76
	v_mov_b32_e32 v95, v79
	v_pk_add_f32 v[84:85], v[84:85], v[94:95]
	v_add_f32_e32 v1, v2, v3
	v_pk_add_f32 v[84:85], v[84:85], v[84:85] op_sel:[0,1] op_sel_hi:[1,0]
	v_add_f32_e32 v2, 0, v1
	s_waitcnt vmcnt(1)
	v_add_f32_e32 v94, v72, v73
	v_add_f32_e32 v104, v74, v75
	s_waitcnt vmcnt(0)
	v_mov_b32_e32 v3, v68
	v_mov_b32_e32 v85, v69
	v_mov_b32_e32 v95, v70
	v_mov_b32_e32 v105, v71
	v_pk_add_f32 v[2:3], v[2:3], v[84:85]
	v_pk_add_f32 v[84:85], v[94:95], v[104:105]
	s_nop 0
	v_pk_add_f32 v[2:3], v[2:3], v[84:85]
	s_nop 0
	v_add_f32_e32 v1, v2, v3
	ds_bpermute_b32 v2, v97, v1
	s_waitcnt lgkmcnt(0)
	v_add_f32_e32 v1, v1, v2
	ds_bpermute_b32 v2, v98, v1
	s_waitcnt lgkmcnt(0)
	v_add_f32_e32 v1, v1, v2
	ds_bpermute_b32 v2, v99, v1
	s_waitcnt lgkmcnt(0)
	v_add_f32_e32 v1, v1, v2
	ds_bpermute_b32 v2, v100, v1
	s_waitcnt lgkmcnt(0)
	v_add_f32_e32 v1, v1, v2
	ds_bpermute_b32 v2, v101, v1
	s_waitcnt lgkmcnt(0)
	v_add_f32_e32 v1, v1, v2
	ds_bpermute_b32 v2, v102, v1
	s_waitcnt lgkmcnt(0)
	v_add_f32_e32 v1, v1, v2
	v_fmamk_f32 v3, v1, 0xba800000, v83
	v_fmamk_f32 v81, v1, 0xba800000, v81
	v_fmamk_f32 v2, v1, 0xba800000, v82
	v_fmac_f32_e32 v80, 0xba800000, v1
	v_mul_f32_e32 v82, v81, v81
	v_mul_f32_e32 v83, v3, v3
	v_fmac_f32_e32 v82, v80, v80
	v_fmac_f32_e32 v83, v2, v2
	v_add_f32_e32 v84, v82, v83
	v_fmamk_f32 v83, v1, 0xba800000, v79
	v_fmamk_f32 v77, v1, 0xba800000, v77
	v_fmamk_f32 v82, v1, 0xba800000, v78
	v_fmac_f32_e32 v76, 0xba800000, v1
	v_mul_f32_e32 v78, v77, v77
	v_mul_f32_e32 v79, v83, v83
	v_fmac_f32_e32 v78, v76, v76
	v_fmac_f32_e32 v79, v82, v82
	v_add_f32_e32 v78, v78, v79
	v_fmamk_f32 v85, v1, 0xba800000, v75
	v_fmamk_f32 v73, v1, 0xba800000, v73
	v_add_f32_e32 v78, v84, v78
	v_fmamk_f32 v84, v1, 0xba800000, v74
	v_fmac_f32_e32 v72, 0xba800000, v1
	v_mul_f32_e32 v74, v73, v73
	v_mul_f32_e32 v75, v85, v85
	v_fmamk_f32 v95, v1, 0xba800000, v71
	v_fmamk_f32 v69, v1, 0xba800000, v69
	v_fmac_f32_e32 v74, v72, v72
	v_fmac_f32_e32 v75, v84, v84
	v_fmamk_f32 v94, v1, 0xba800000, v70
	v_fmac_f32_e32 v68, 0xba800000, v1
	v_mul_f32_e32 v70, v69, v69
	v_mul_f32_e32 v71, v95, v95
	v_add_f32_e32 v74, v74, v75
	v_fmac_f32_e32 v70, v68, v68
	v_fmac_f32_e32 v71, v94, v94
	v_add_f32_e32 v74, v74, v78
	v_add_f32_e32 v70, v70, v71
	v_add_f32_e32 v70, v70, v74
	ds_bpermute_b32 v71, v97, v70
	s_waitcnt lgkmcnt(0)
	v_add_f32_e32 v70, v70, v71
	ds_bpermute_b32 v71, v98, v70
	s_waitcnt lgkmcnt(0)
	v_add_f32_e32 v70, v70, v71
	ds_bpermute_b32 v71, v99, v70
	s_waitcnt lgkmcnt(0)
	v_add_f32_e32 v70, v70, v71
	ds_bpermute_b32 v71, v100, v70
	s_waitcnt lgkmcnt(0)
	v_add_f32_e32 v70, v70, v71
	ds_bpermute_b32 v71, v101, v70
	s_waitcnt lgkmcnt(0)
	v_add_f32_e32 v70, v70, v71
	ds_bpermute_b32 v71, v102, v70
	s_waitcnt lgkmcnt(0)
	v_add_f32_e32 v70, v70, v71
	v_fmamk_f32 v70, v70, 0x3a800000, v228
	v_cmp_gt_f32_e32 vcc, s49, v70
	v_mul_f32_e32 v71, 0x4f800000, v70
	s_nop 0
	v_cndmask_b32_e32 v70, v70, v71, vcc
	v_sqrt_f32_e32 v71, v70
	s_nop 0
	v_add_u32_e32 v74, -1, v71
	v_fma_f32 v75, -v74, v71, v70
	v_cmp_ge_f32_e64 s[0:1], 0, v75
	v_add_u32_e32 v75, 1, v71
	s_nop 0
	v_cndmask_b32_e64 v74, v71, v74, s[0:1]
	v_fma_f32 v71, -v75, v71, v70
	v_cmp_lt_f32_e64 s[0:1], 0, v71
	s_nop 1
	v_cndmask_b32_e64 v71, v74, v75, s[0:1]
	v_mul_f32_e32 v74, 0x37800000, v71
	v_cndmask_b32_e32 v71, v71, v74, vcc
	v_cmp_class_f32_e32 vcc, v70, v229
	s_nop 1
	v_cndmask_b32_e32 v70, v71, v70, vcc
	v_div_scale_f32 v71, s[0:1], v70, v70, 1.0
	v_rcp_f32_e32 v74, v71
	s_nop 0
	v_fma_f32 v75, -v71, v74, 1.0
	v_fmac_f32_e32 v74, v75, v74
	v_div_scale_f32 v75, vcc, 1.0, v70, 1.0
	v_mul_f32_e32 v78, v75, v74
	v_fma_f32 v79, -v71, v78, v75
	v_fmac_f32_e32 v78, v79, v74
	v_fma_f32 v71, -v71, v78, v75
	v_div_fmas_f32 v71, v71, v74, v78
	v_div_fixup_f32 v96, v71, v70, 1.0
	s_and_saveexec_b64 s[0:1], s[8:9]
	s_cbranch_execz .LBB0_338
	s_add_u32 s18, s4, s13
	v_mul_f32_e32 v70, 0x3a800000, v1
	s_addc_u32 s19, s5, s14
	v_mov_b32_e32 v71, v96
	global_store_dwordx2 v0, v[70:71], s[18:19]

.LBB0_403:
	s_add_i32 s14, s8, 0xffff8000
	s_and_b64 s[4:5], s[4:5], exec
	s_cselect_b32 s5, s9, 0
	s_cselect_b32 s4, s8, s14
	s_cselect_b32 s14, s75, s10
	s_cselect_b32 s15, s74, s2
	s_lshl_b64 s[4:5], s[4:5], 12
	s_add_u32 s4, s15, s4
	s_addc_u32 s5, s14, s5
	global_load_dwordx4 v[80:83], v96, s[4:5]
	global_load_dwordx4 v[76:79], v96, s[4:5] offset:1024
	global_load_dwordx4 v[72:75], v96, s[4:5] offset:2048
	global_load_dwordx4 v[68:71], v96, s[4:5] offset:3072
	s_cmp_lt_i32 s8, 0x8000
	s_cbranch_scc1 .Lfxb_skip
	s_add_u32 s100, s4, 0x17700000
	s_addc_u32 s101, s5, 0
	global_load_dwordx4 v[130:133], v96, s[100:101]
	global_load_dwordx4 v[134:137], v96, s[100:101] offset:1024
	global_load_dwordx4 v[138:141], v96, s[100:101] offset:2048
	global_load_dwordx4 v[142:145], v96, s[100:101] offset:3072
	s_add_u32 s100, s100, 0x200000
	s_addc_u32 s101, s101, 0
	global_load_dwordx4 v[146:149], v96, s[100:101]
	global_load_dwordx4 v[150:153], v96, s[100:101] offset:1024
	global_load_dwordx4 v[154:157], v96, s[100:101] offset:2048
	global_load_dwordx4 v[158:161], v96, s[100:101] offset:3072
	s_add_u32 s100, s100, 0x200000
	s_addc_u32 s101, s101, 0
	global_load_dwordx4 v[162:165], v96, s[100:101]
	global_load_dwordx4 v[166:169], v96, s[100:101] offset:1024
	global_load_dwordx4 v[170:173], v96, s[100:101] offset:2048
	global_load_dwordx4 v[174:177], v96, s[100:101] offset:3072
	s_waitcnt vmcnt(0)
	v_add_f32_e32 v80, v80, v130
	v_add_f32_e32 v81, v81, v131
	v_add_f32_e32 v82, v82, v132
	v_add_f32_e32 v83, v83, v133
	v_add_f32_e32 v76, v76, v134
	v_add_f32_e32 v77, v77, v135
	v_add_f32_e32 v78, v78, v136
	v_add_f32_e32 v79, v79, v137
	v_add_f32_e32 v72, v72, v138
	v_add_f32_e32 v73, v73, v139
	v_add_f32_e32 v74, v74, v140
	v_add_f32_e32 v75, v75, v141
	v_add_f32_e32 v68, v68, v142
	v_add_f32_e32 v69, v69, v143
	v_add_f32_e32 v70, v70, v144
	v_add_f32_e32 v71, v71, v145
	v_add_f32_e32 v80, v80, v146
	v_add_f32_e32 v81, v81, v147
	v_add_f32_e32 v82, v82, v148
	v_add_f32_e32 v83, v83, v149
	v_add_f32_e32 v76, v76, v150
	v_add_f32_e32 v77, v77, v151
	v_add_f32_e32 v78, v78, v152
	v_add_f32_e32 v79, v79, v153
	v_add_f32_e32 v72, v72, v154
	v_add_f32_e32 v73, v73, v155
	v_add_f32_e32 v74, v74, v156
	v_add_f32_e32 v75, v75, v157
	v_add_f32_e32 v68, v68, v158
	v_add_f32_e32 v69, v69, v159
	v_add_f32_e32 v70, v70, v160
	v_add_f32_e32 v71, v71, v161
	v_add_f32_e32 v80, v80, v162
	v_add_f32_e32 v81, v81, v163
	v_add_f32_e32 v82, v82, v164
	v_add_f32_e32 v83, v83, v165
	v_add_f32_e32 v76, v76, v166
	v_add_f32_e32 v77, v77, v167
	v_add_f32_e32 v78, v78, v168
	v_add_f32_e32 v79, v79, v169
	v_add_f32_e32 v72, v72, v170
	v_add_f32_e32 v73, v73, v171
	v_add_f32_e32 v74, v74, v172
	v_add_f32_e32 v75, v75, v173
	v_add_f32_e32 v68, v68, v174
	v_add_f32_e32 v69, v69, v175
	v_add_f32_e32 v70, v70, v176
	v_add_f32_e32 v71, v71, v177
	global_store_dwordx4 v96, v[80:83], s[4:5]
	global_store_dwordx4 v96, v[76:79], s[4:5] offset:1024
	global_store_dwordx4 v96, v[72:75], s[4:5] offset:2048
	global_store_dwordx4 v96, v[68:71], s[4:5] offset:3072
	s_nop 1
.Lfxb_skip:
	s_waitcnt vmcnt(3)
	v_mov_b32_e32 v2, v81
	v_mov_b32_e32 v3, v82
	v_mov_b32_e32 v98, v80
	v_mov_b32_e32 v99, v83
	v_pk_add_f32 v[2:3], v[2:3], v[98:99]
	s_waitcnt vmcnt(2)
	v_mov_b32_e32 v98, v77
	v_mov_b32_e32 v99, v78
	v_mov_b32_e32 v100, v76
	v_mov_b32_e32 v101, v79
	v_pk_add_f32 v[98:99], v[98:99], v[100:101]
	v_add_f32_e32 v1, v2, v3
	v_pk_add_f32 v[98:99], v[98:99], v[98:99] op_sel:[0,1] op_sel_hi:[1,0]
	v_add_f32_e32 v2, 0, v1
	s_waitcnt vmcnt(1)
	v_add_f32_e32 v100, v72, v73
	v_add_f32_e32 v102, v74, v75
	s_waitcnt vmcnt(0)
	v_mov_b32_e32 v3, v68
	v_mov_b32_e32 v99, v69
	v_mov_b32_e32 v101, v70
	v_mov_b32_e32 v103, v71
	v_pk_add_f32 v[2:3], v[2:3], v[98:99]
	v_pk_add_f32 v[98:99], v[100:101], v[102:103]
	s_nop 0
	v_pk_add_f32 v[2:3], v[2:3], v[98:99]
	s_nop 0
	v_add_f32_e32 v1, v2, v3
	ds_bpermute_b32 v2, v90, v1
	s_waitcnt lgkmcnt(0)
	v_add_f32_e32 v1, v1, v2
	ds_bpermute_b32 v2, v91, v1
	s_waitcnt lgkmcnt(0)
	v_add_f32_e32 v1, v1, v2
	ds_bpermute_b32 v2, v92, v1
	s_waitcnt lgkmcnt(0)
	v_add_f32_e32 v1, v1, v2
	ds_bpermute_b32 v2, v93, v1
	s_waitcnt lgkmcnt(0)
	v_add_f32_e32 v1, v1, v2
	ds_bpermute_b32 v2, v94, v1
	s_waitcnt lgkmcnt(0)
	v_add_f32_e32 v1, v1, v2
	ds_bpermute_b32 v2, v95, v1
	s_waitcnt lgkmcnt(0)
	v_add_f32_e32 v1, v1, v2
	v_fmamk_f32 v3, v1, 0xba800000, v83
	v_fmamk_f32 v81, v1, 0xba800000, v81
	v_fmamk_f32 v2, v1, 0xba800000, v82
	v_fmac_f32_e32 v80, 0xba800000, v1
	v_mul_f32_e32 v82, v81, v81
	v_mul_f32_e32 v83, v3, v3
	v_fmac_f32_e32 v82, v80, v80
	v_fmac_f32_e32 v83, v2, v2
	v_fmamk_f32 v79, v1, 0xba800000, v79
	v_fmamk_f32 v77, v1, 0xba800000, v77
	v_add_f32_e32 v82, v82, v83
	v_fmamk_f32 v78, v1, 0xba800000, v78
	v_fmac_f32_e32 v76, 0xba800000, v1
	v_mul_f32_e32 v83, v77, v77
	v_mul_f32_e32 v97, v79, v79
	v_fmac_f32_e32 v83, v76, v76
	v_fmac_f32_e32 v97, v78, v78
	v_add_f32_e32 v83, v83, v97
	v_fmamk_f32 v75, v1, 0xba800000, v75
	v_fmamk_f32 v73, v1, 0xba800000, v73
	v_add_f32_e32 v82, v82, v83
	v_fmamk_f32 v74, v1, 0xba800000, v74
	v_fmac_f32_e32 v72, 0xba800000, v1
	v_mul_f32_e32 v83, v73, v73
	v_mul_f32_e32 v97, v75, v75
	v_fmac_f32_e32 v83, v72, v72
	v_fmac_f32_e32 v97, v74, v74
	v_add_f32_e32 v83, v83, v97
	v_fmamk_f32 v71, v1, 0xba800000, v71
	v_fmamk_f32 v69, v1, 0xba800000, v69
	v_add_f32_e32 v82, v83, v82
	v_fmamk_f32 v70, v1, 0xba800000, v70
	v_fmac_f32_e32 v68, 0xba800000, v1
	v_mul_f32_e32 v83, v69, v69
	v_mul_f32_e32 v97, v71, v71
	v_fmac_f32_e32 v83, v68, v68
	v_fmac_f32_e32 v97, v70, v70
	v_add_f32_e32 v83, v83, v97
	v_add_f32_e32 v82, v83, v82
	ds_bpermute_b32 v83, v90, v82
	s_waitcnt lgkmcnt(0)
	v_add_f32_e32 v82, v82, v83
	ds_bpermute_b32 v83, v91, v82
	s_waitcnt lgkmcnt(0)
	v_add_f32_e32 v82, v82, v83
	ds_bpermute_b32 v83, v92, v82
	s_waitcnt lgkmcnt(0)
	v_add_f32_e32 v82, v82, v83
	ds_bpermute_b32 v83, v93, v82
	s_waitcnt lgkmcnt(0)
	v_add_f32_e32 v82, v82, v83
	ds_bpermute_b32 v83, v94, v82
	s_waitcnt lgkmcnt(0)
	v_add_f32_e32 v82, v82, v83
	ds_bpermute_b32 v83, v95, v82
	s_waitcnt lgkmcnt(0)
	v_add_f32_e32 v82, v82, v83
	v_fmamk_f32 v82, v82, 0x3a800000, v228
	v_cmp_gt_f32_e32 vcc, s49, v82
	v_mul_f32_e32 v83, 0x4f800000, v82
	s_nop 0
	v_cndmask_b32_e32 v82, v82, v83, vcc
	v_sqrt_f32_e32 v83, v82
	s_nop 0
	v_add_u32_e32 v97, -1, v83
	v_fma_f32 v98, -v97, v83, v82
	v_cmp_ge_f32_e64 s[4:5], 0, v98
	v_add_u32_e32 v98, 1, v83
	s_nop 0
	v_cndmask_b32_e64 v97, v83, v97, s[4:5]
	v_fma_f32 v83, -v98, v83, v82
	v_cmp_lt_f32_e64 s[4:5], 0, v83
	s_nop 1
	v_cndmask_b32_e64 v83, v97, v98, s[4:5]
	v_mul_f32_e32 v97, 0x37800000, v83
	v_cndmask_b32_e32 v83, v83, v97, vcc
	v_cmp_class_f32_e32 vcc, v82, v229
	s_nop 1
	v_cndmask_b32_e32 v82, v83, v82, vcc
	v_div_scale_f32 v83, s[4:5], v82, v82, 1.0
	v_rcp_f32_e32 v97, v83
	s_nop 0
	v_fma_f32 v98, -v83, v97, 1.0
	v_fmac_f32_e32 v97, v98, v97
	v_div_scale_f32 v98, vcc, 1.0, v82, 1.0
	v_mul_f32_e32 v99, v98, v97
	v_fma_f32 v100, -v83, v99, v98
	v_fmac_f32_e32 v99, v100, v97
	v_fma_f32 v83, -v83, v99, v98
	v_div_fmas_f32 v83, v83, v97, v99
	v_div_fixup_f32 v82, v83, v82, 1.0
	s_and_saveexec_b64 s[4:5], s[0:1]
	s_cbranch_execz .LBB0_400
	s_add_u32 s14, s6, s11
	v_mul_f32_e32 v98, 0x3a800000, v1
	s_addc_u32 s15, s7, s12
	v_mov_b32_e32 v99, v82
	global_store_dwordx2 v0, v[98:99], s[14:15]
	s_branch .LBB0_400

	.amdhsa_kernel _Z8mega_fwd6Params
		.amdhsa_group_segment_fixed_size 0
		.amdhsa_private_segment_fixed_size 0
		.amdhsa_kernarg_size 456
		.amdhsa_user_sgpr_count 2
		.amdhsa_user_sgpr_dispatch_ptr 0
		.amdhsa_user_sgpr_queue_ptr 0
		.amdhsa_user_sgpr_kernarg_segment_ptr 1
		.amdhsa_user_sgpr_dispatch_id 0
		.amdhsa_user_sgpr_kernarg_preload_length 0
		.amdhsa_user_sgpr_kernarg_preload_offset 0
		.amdhsa_user_sgpr_private_segment_size 0
		.amdhsa_uses_dynamic_stack 0
		.amdhsa_enable_private_segment 0
		.amdhsa_system_sgpr_workgroup_id_x 1
		.amdhsa_system_sgpr_workgroup_id_y 0
		.amdhsa_system_sgpr_workgroup_id_z 0
		.amdhsa_system_sgpr_workgroup_info 0
		.amdhsa_system_vgpr_workitem_id 2
		.amdhsa_next_free_vgpr 256
		.amdhsa_next_free_sgpr 102
		.amdhsa_accum_offset 256
		.amdhsa_reserve_vcc 1
		.amdhsa_float_round_mode_32 0
		.amdhsa_float_round_mode_16_64 0
		.amdhsa_float_denorm_mode_32 3
		.amdhsa_float_denorm_mode_16_64 3
		.amdhsa_dx10_clamp 1
		.amdhsa_ieee_mode 1
		.amdhsa_fp16_overflow 0
		.amdhsa_tg_split 0
		.amdhsa_exception_fp_ieee_invalid_op 0
		.amdhsa_exception_fp_denorm_src 0
		.amdhsa_exception_fp_ieee_div_zero 0
		.amdhsa_exception_fp_ieee_overflow 0
		.amdhsa_exception_fp_ieee_underflow 0
		.amdhsa_exception_fp_ieee_inexact 0
		.amdhsa_exception_int_div_zero 0
	.end_amdhsa_kernel

amdhsa.kernels:
  - .agpr_count:     0
    .args:
      - .offset:         0
        .size:           200
        .value_kind:     by_value
      - .offset:         200
        .size:           4
        .value_kind:     hidden_block_count_x
      - .offset:         204
        .size:           4
        .value_kind:     hidden_block_count_y
      - .offset:         208
        .size:           4
        .value_kind:     hidden_block_count_z
      - .offset:         212
        .size:           2
        .value_kind:     hidden_group_size_x
      - .offset:         214
        .size:           2
        .value_kind:     hidden_group_size_y
      - .offset:         216
        .size:           2
        .value_kind:     hidden_group_size_z
      - .offset:         218
        .size:           2
        .value_kind:     hidden_remainder_x
      - .offset:         220
        .size:           2
        .value_kind:     hidden_remainder_y
      - .offset:         222
        .size:           2
        .value_kind:     hidden_remainder_z
      - .offset:         240
        .size:           8
        .value_kind:     hidden_global_offset_x
      - .offset:         248
        .size:           8
        .value_kind:     hidden_global_offset_y
      - .offset:         256
        .size:           8
        .value_kind:     hidden_global_offset_z
      - .offset:         264
        .size:           2
        .value_kind:     hidden_grid_dims
      - .offset:         288
        .size:           8
        .value_kind:     hidden_multigrid_sync_arg
      - .offset:         320
        .size:           4
        .value_kind:     hidden_dynamic_lds_size
    .group_segment_fixed_size: 0
    .kernarg_segment_align: 8
    .kernarg_segment_size: 456
    .language:       OpenCL C
    .language_version:
      - 2
      - 0
    .max_flat_workgroup_size: 512
    .name:           _Z8mega_fwd6Params
    .private_segment_fixed_size: 0
    .sgpr_count:     108
    .sgpr_spill_count: 213
    .symbol:         _Z8mega_fwd6Params.kd
    .uniform_work_group_size: 1
    .uses_dynamic_stack: false
    .vgpr_count:     256
    .vgpr_spill_count: 0
    .wavefront_size: 64
